# FFT pair final loop: the 32 two-byte loads of an iteration issued together before one wait (hipcc kept only 2-3 in flight)
# speedup vs baseline: 1.0373x; 1.0062x over previous
.LBB0_704:
	v_add_u32_e32 v152, s20, v24
	v_ashrrev_i32_e32 v153, 31, v152
	v_lshlrev_b64 v[148:149], 1, v[152:153]
	v_lshl_add_u64 v[150:151], s[30:31], 0, v[148:149]
	global_load_ushort v116, v[150:151], off
	v_add_u32_e32 v150, s20, v24
	v_ashrrev_i32_e32 v151, 31, v150
	v_lshl_add_u64 v[148:149], s[2:3], 0, v[150:151]
	v_lshl_add_u64 v[148:149], v[148:149], 1, s[0:1]
	global_load_ushort v117, v[148:149], off
	v_add_u32_e32 v150, s20, v24
	v_ashrrev_i32_e32 v151, 31, v150
	v_lshlrev_b64 v[148:149], 1, v[150:151]
	v_lshl_add_u64 v[148:149], s[86:87], 0, v[148:149]
	global_load_ushort v118, v[148:149], off
	v_add_u32_e32 v152, s20, v24
	v_add_u32_e32 v148, 0xe00, v152
	v_ashrrev_i32_e32 v149, 31, v148
	v_lshl_add_u64 v[150:151], s[2:3], 0, v[148:149]
	v_lshl_add_u64 v[150:151], v[150:151], 1, s[0:1]
	global_load_ushort v119, v[150:151], off
	v_add_u32_e32 v152, s20, v24
	v_ashrrev_i32_e32 v153, 31, v152
	v_lshl_add_u64 v[150:151], s[10:11], 0, v[152:153]
	v_lshl_add_u64 v[148:149], v[150:151], 1, s[0:1]
	global_load_ushort v120, v[148:149], off
	v_add_u32_e32 v152, s20, v24
	v_add_u32_e32 v150, 0x200, v152
	v_ashrrev_i32_e32 v151, 31, v150
	v_lshl_add_u64 v[148:149], s[2:3], 0, v[150:151]
	v_lshl_add_u64 v[148:149], v[148:149], 1, s[0:1]
	global_load_ushort v121, v[148:149], off
	v_add_u32_e32 v152, s20, v24
	v_add_u32_e32 v148, 0xe00, v152
	v_ashrrev_i32_e32 v149, 31, v148
	v_lshl_add_u64 v[150:151], s[10:11], 0, v[148:149]
	v_lshl_add_u64 v[150:151], v[150:151], 1, s[0:1]
	global_load_ushort v122, v[150:151], off
	v_add_u32_e32 v154, s20, v24
	v_add_u32_e32 v152, 0x200, v154
	v_ashrrev_i32_e32 v153, 31, v152
	v_lshlrev_b64 v[148:149], 1, v[152:153]
	v_lshl_add_u64 v[150:151], s[30:31], 0, v[148:149]
	global_load_ushort v123, v[150:151], off
	v_add_u32_e32 v154, s20, v24
	v_add_u32_e32 v152, 0x200, v154
	v_ashrrev_i32_e32 v153, 31, v152
	v_lshl_add_u64 v[150:151], s[10:11], 0, v[152:153]
	v_lshl_add_u64 v[148:149], v[150:151], 1, s[0:1]
	global_load_ushort v124, v[148:149], off
	v_add_u32_e32 v152, s20, v24
	v_add_u32_e32 v150, 0x400, v152
	v_ashrrev_i32_e32 v151, 31, v150
	v_lshl_add_u64 v[148:149], s[2:3], 0, v[150:151]
	v_lshl_add_u64 v[148:149], v[148:149], 1, s[0:1]
	global_load_ushort v125, v[148:149], off
	v_add_u32_e32 v152, s20, v24
	v_add_u32_e32 v150, 0x200, v152
	v_ashrrev_i32_e32 v151, 31, v150
	v_lshlrev_b64 v[148:149], 1, v[150:151]
	v_lshl_add_u64 v[148:149], s[86:87], 0, v[148:149]
	global_load_ushort v126, v[148:149], off
	v_add_u32_e32 v154, s20, v24
	v_add_u32_e32 v152, 0x400, v154
	v_ashrrev_i32_e32 v153, 31, v152
	v_lshlrev_b64 v[148:149], 1, v[152:153]
	v_lshl_add_u64 v[150:151], s[30:31], 0, v[148:149]
	global_load_ushort v127, v[150:151], off
	v_add_u32_e32 v152, s20, v24
	v_add_u32_e32 v150, 0x400, v152
	v_ashrrev_i32_e32 v151, 31, v150
	v_lshlrev_b64 v[148:149], 1, v[150:151]
	v_lshl_add_u64 v[148:149], s[86:87], 0, v[148:149]
	global_load_ushort v128, v[148:149], off
	v_add_u32_e32 v154, s20, v24
	v_add_u32_e32 v152, 0x400, v154
	v_ashrrev_i32_e32 v153, 31, v152
	v_lshl_add_u64 v[150:151], s[10:11], 0, v[152:153]
	v_lshl_add_u64 v[148:149], v[150:151], 1, s[0:1]
	global_load_ushort v129, v[148:149], off
	v_add_u32_e32 v152, s20, v24
	v_add_u32_e32 v150, 0x600, v152
	v_ashrrev_i32_e32 v151, 31, v150
	v_lshl_add_u64 v[148:149], s[2:3], 0, v[150:151]
	v_lshl_add_u64 v[148:149], v[148:149], 1, s[0:1]
	global_load_ushort v130, v[148:149], off
	v_add_u32_e32 v154, s20, v24
	v_add_u32_e32 v152, 0x600, v154
	v_ashrrev_i32_e32 v153, 31, v152
	v_lshlrev_b64 v[148:149], 1, v[152:153]
	v_lshl_add_u64 v[150:151], s[30:31], 0, v[148:149]
	global_load_ushort v131, v[150:151], off
	v_add_u32_e32 v154, s20, v24
	v_add_u32_e32 v152, 0x600, v154
	v_ashrrev_i32_e32 v153, 31, v152
	v_lshl_add_u64 v[150:151], s[10:11], 0, v[152:153]
	v_lshl_add_u64 v[148:149], v[150:151], 1, s[0:1]
	global_load_ushort v132, v[148:149], off
	v_add_u32_e32 v152, s20, v24
	v_add_u32_e32 v150, 0x600, v152
	v_ashrrev_i32_e32 v151, 31, v150
	v_lshlrev_b64 v[148:149], 1, v[150:151]
	v_lshl_add_u64 v[148:149], s[86:87], 0, v[148:149]
	global_load_ushort v133, v[148:149], off
	v_add_u32_e32 v152, s20, v24
	v_add_u32_e32 v150, 0x800, v152
	v_ashrrev_i32_e32 v151, 31, v150
	v_lshl_add_u64 v[148:149], s[2:3], 0, v[150:151]
	v_lshl_add_u64 v[148:149], v[148:149], 1, s[0:1]
	global_load_ushort v134, v[148:149], off
	v_add_u32_e32 v154, s20, v24
	v_add_u32_e32 v152, 0x800, v154
	v_ashrrev_i32_e32 v153, 31, v152
	v_lshlrev_b64 v[148:149], 1, v[152:153]
	v_lshl_add_u64 v[150:151], s[30:31], 0, v[148:149]
	global_load_ushort v135, v[150:151], off
	v_add_u32_e32 v154, s20, v24
	v_add_u32_e32 v152, 0x800, v154
	v_ashrrev_i32_e32 v153, 31, v152
	v_lshl_add_u64 v[150:151], s[10:11], 0, v[152:153]
	v_lshl_add_u64 v[148:149], v[150:151], 1, s[0:1]
	global_load_ushort v136, v[148:149], off
	v_add_u32_e32 v152, s20, v24
	v_add_u32_e32 v150, 0x800, v152
	v_ashrrev_i32_e32 v151, 31, v150
	v_lshlrev_b64 v[148:149], 1, v[150:151]
	v_lshl_add_u64 v[148:149], s[86:87], 0, v[148:149]
	global_load_ushort v137, v[148:149], off
	v_add_u32_e32 v152, s20, v24
	v_add_u32_e32 v150, 0xa00, v152
	v_ashrrev_i32_e32 v151, 31, v150
	v_lshl_add_u64 v[148:149], s[2:3], 0, v[150:151]
	v_lshl_add_u64 v[148:149], v[148:149], 1, s[0:1]
	global_load_ushort v138, v[148:149], off
	v_add_u32_e32 v154, s20, v24
	v_add_u32_e32 v152, 0xa00, v154
	v_ashrrev_i32_e32 v153, 31, v152
	v_lshlrev_b64 v[148:149], 1, v[152:153]
	v_lshl_add_u64 v[150:151], s[30:31], 0, v[148:149]
	global_load_ushort v139, v[150:151], off
	v_add_u32_e32 v154, s20, v24
	v_add_u32_e32 v152, 0xa00, v154
	v_ashrrev_i32_e32 v153, 31, v152
	v_lshl_add_u64 v[150:151], s[10:11], 0, v[152:153]
	v_lshl_add_u64 v[148:149], v[150:151], 1, s[0:1]
	global_load_ushort v140, v[148:149], off
	v_add_u32_e32 v152, s20, v24
	v_add_u32_e32 v150, 0xa00, v152
	v_ashrrev_i32_e32 v151, 31, v150
	v_lshlrev_b64 v[148:149], 1, v[150:151]
	v_lshl_add_u64 v[148:149], s[86:87], 0, v[148:149]
	global_load_ushort v141, v[148:149], off
	v_add_u32_e32 v152, s20, v24
	v_add_u32_e32 v150, 0xc00, v152
	v_ashrrev_i32_e32 v151, 31, v150
	v_lshl_add_u64 v[148:149], s[2:3], 0, v[150:151]
	v_lshl_add_u64 v[148:149], v[148:149], 1, s[0:1]
	global_load_ushort v142, v[148:149], off
	v_add_u32_e32 v154, s20, v24
	v_add_u32_e32 v152, 0xc00, v154
	v_ashrrev_i32_e32 v153, 31, v152
	v_lshlrev_b64 v[148:149], 1, v[152:153]
	v_lshl_add_u64 v[150:151], s[30:31], 0, v[148:149]
	global_load_ushort v143, v[150:151], off
	v_add_u32_e32 v152, s20, v24
	v_add_u32_e32 v150, 0xc00, v152
	v_ashrrev_i32_e32 v151, 31, v150
	v_lshlrev_b64 v[148:149], 1, v[150:151]
	v_lshl_add_u64 v[148:149], s[86:87], 0, v[148:149]
	global_load_ushort v144, v[148:149], off
	v_add_u32_e32 v154, s20, v24
	v_add_u32_e32 v152, 0xc00, v154
	v_ashrrev_i32_e32 v153, 31, v152
	v_lshl_add_u64 v[150:151], s[10:11], 0, v[152:153]
	v_lshl_add_u64 v[148:149], v[150:151], 1, s[0:1]
	global_load_ushort v145, v[148:149], off
	v_add_u32_e32 v154, s20, v24
	v_add_u32_e32 v152, 0xe00, v154
	v_ashrrev_i32_e32 v153, 31, v152
	v_lshlrev_b64 v[148:149], 1, v[152:153]
	v_lshl_add_u64 v[150:151], s[30:31], 0, v[148:149]
	global_load_ushort v146, v[150:151], off
	v_add_u32_e32 v152, s20, v24
	v_add_u32_e32 v150, 0xe00, v152
	v_ashrrev_i32_e32 v151, 31, v150
	v_lshlrev_b64 v[148:149], 1, v[150:151]
	v_lshl_add_u64 v[148:149], s[86:87], 0, v[148:149]
	global_load_ushort v147, v[148:149], off
	s_waitcnt vmcnt(0)
	v_add_u32_e32 v82, s20, v24
	v_ashrrev_i32_e32 v83, 31, v82
	v_lshlrev_b64 v[4:5], 1, v[82:83]
	v_lshl_add_u64 v[20:21], s[30:31], 0, v[4:5]
	v_lshl_add_u64 v[6:7], s[2:3], 0, v[82:83]
	v_lshl_add_u64 v[4:5], s[86:87], 0, v[4:5]
	v_lshl_add_u64 v[6:7], v[6:7], 1, s[0:1]
	v_add_u32_e32 v54, 0xe00, v82
	v_ashrrev_i32_e32 v55, 31, v54
	v_lshl_add_u64 v[80:81], s[2:3], 0, v[54:55]
	v_lshl_add_u64 v[8:9], s[10:11], 0, v[82:83]
	v_lshl_add_u64 v[80:81], v[80:81], 1, s[0:1]
	v_add_u32_e32 v42, 0x200, v82
	v_ashrrev_i32_e32 v43, 31, v42
	v_lshl_add_u64 v[114:115], s[10:11], 0, v[54:55]
	v_lshl_add_u64 v[114:115], v[114:115], 1, s[0:1]
	v_add_u32_e32 v44, 0x400, v82
	v_ashrrev_i32_e32 v45, 31, v44
	v_add_u32_e32 v46, 0x600, v82
	v_ashrrev_i32_e32 v47, 31, v46
	v_add_u32_e32 v48, 0x800, v82
	v_ashrrev_i32_e32 v49, 31, v48
	v_add_u32_e32 v50, 0xa00, v82
	v_ashrrev_i32_e32 v51, 31, v50
	v_add_u32_e32 v52, 0xc00, v82
	v_ashrrev_i32_e32 v53, 31, v52
	v_lshl_add_u64 v[40:41], s[10:11], 0, v[52:53]
	v_lshl_add_u32 v111, s20, 3, v90
	s_movk_i32 s20, 0x1000
	s_and_b64 vcc, exec, s[12:13]
	s_mov_b64 s[12:13], 0
	v_lshlrev_b32_e32 v57, 16, v116
	v_ashrrev_i32_e32 v81, 5, v82
	v_lshl_add_u32 v81, v81, 3, v111
	ds_read_b64 v[82:83], v81
	s_waitcnt lgkmcnt(0)
	v_mul_f32_e32 v81, 0x38800000, v82
	v_mul_f32_e32 v81, v0, v81
	v_fmac_f32_e32 v81, v2, v57
	v_lshlrev_b32_e32 v73, 16, v117
	v_lshl_add_u64 v[6:7], v[8:9], 1, s[0:1]
	v_lshl_add_u64 v[8:9], s[2:3], 0, v[42:43]
	v_lshl_add_u64 v[8:9], v[8:9], 1, s[0:1]
	v_mul_f32_e32 v57, v81, v73
	v_bfe_u32 v73, v57, 16, 1
	v_add3_u32 v57, v57, v73, s45
	v_lshlrev_b32_e32 v56, 16, v118
	v_lshlrev_b32_e32 v80, 16, v119
	v_lshl_add_u64 v[10:11], s[10:11], 0, v[42:43]
	v_lshlrev_b32_e32 v65, 16, v120
	v_lshlrev_b64 v[6:7], 1, v[42:43]
	v_lshl_add_u64 v[22:23], s[30:31], 0, v[6:7]
	v_lshl_add_u64 v[6:7], s[86:87], 0, v[6:7]
	v_lshlrev_b32_e32 v74, 16, v121
	v_lshl_add_u64 v[8:9], v[10:11], 1, s[0:1]
	v_lshl_add_u64 v[10:11], s[2:3], 0, v[44:45]
	v_lshl_add_u64 v[10:11], v[10:11], 1, s[0:1]
	v_lshlrev_b32_e32 v72, 16, v122
	v_lshlrev_b32_e32 v58, 16, v123
	v_lshlrev_b32_e32 v66, 16, v124
	v_lshlrev_b64 v[8:9], 1, v[44:45]
	v_lshl_add_u64 v[30:31], s[30:31], 0, v[8:9]
	v_lshl_add_u64 v[8:9], s[86:87], 0, v[8:9]
	v_lshlrev_b32_e32 v75, 16, v125
	v_lshlrev_b32_e32 v43, 16, v126
	v_lshl_add_u64 v[12:13], s[10:11], 0, v[44:45]
	v_lshl_add_u64 v[10:11], v[12:13], 1, s[0:1]
	v_lshl_add_u64 v[12:13], s[2:3], 0, v[46:47]
	v_lshl_add_u64 v[12:13], v[12:13], 1, s[0:1]
	v_lshlrev_b32_e32 v59, 16, v127
	s_nop 0
	s_nop 0
	v_lshlrev_b32_e32 v45, 16, v128
	v_lshl_add_u64 v[14:15], s[10:11], 0, v[46:47]
	v_lshlrev_b32_e32 v67, 16, v129
	v_lshlrev_b64 v[10:11], 1, v[46:47]
	v_lshlrev_b32_e32 v76, 16, v130
	v_lshl_add_u64 v[32:33], s[30:31], 0, v[10:11]
	v_lshl_add_u64 v[10:11], s[86:87], 0, v[10:11]
	v_lshl_add_u64 v[12:13], v[14:15], 1, s[0:1]
	v_lshl_add_u64 v[14:15], s[2:3], 0, v[48:49]
	v_lshl_add_u64 v[14:15], v[14:15], 1, s[0:1]
	v_lshlrev_b32_e32 v60, 16, v131
	s_nop 0
	v_lshlrev_b32_e32 v68, 16, v132
	v_lshlrev_b64 v[12:13], 1, v[48:49]
	v_lshl_add_u64 v[34:35], s[30:31], 0, v[12:13]
	v_lshl_add_u64 v[12:13], s[86:87], 0, v[12:13]
	v_lshlrev_b32_e32 v47, 16, v133
	v_lshl_add_u64 v[16:17], s[10:11], 0, v[48:49]
	v_lshlrev_b32_e32 v77, 16, v134
	v_lshl_add_u64 v[14:15], v[16:17], 1, s[0:1]
	v_lshl_add_u64 v[16:17], s[2:3], 0, v[50:51]
	v_lshl_add_u64 v[16:17], v[16:17], 1, s[0:1]
	v_lshlrev_b32_e32 v61, 16, v135
	s_nop 0
	v_lshlrev_b32_e32 v69, 16, v136
	v_lshlrev_b64 v[14:15], 1, v[50:51]
	v_lshlrev_b32_e32 v49, 16, v137
	v_lshl_add_u64 v[18:19], s[10:11], 0, v[50:51]
	v_lshlrev_b32_e32 v78, 16, v138
	v_lshl_add_u64 v[36:37], s[30:31], 0, v[14:15]
	v_lshl_add_u64 v[14:15], s[86:87], 0, v[14:15]
	v_lshl_add_u64 v[16:17], v[18:19], 1, s[0:1]
	v_lshl_add_u64 v[18:19], s[2:3], 0, v[52:53]
	v_lshl_add_u64 v[18:19], v[18:19], 1, s[0:1]
	v_lshlrev_b32_e32 v62, 16, v139
	s_nop 0
	v_lshlrev_b32_e32 v70, 16, v140
	v_lshlrev_b64 v[16:17], 1, v[52:53]
	v_lshlrev_b32_e32 v51, 16, v141
	v_lshl_add_u64 v[38:39], s[30:31], 0, v[16:17]
	v_lshl_add_u64 v[16:17], s[86:87], 0, v[16:17]
	v_lshlrev_b32_e32 v79, 16, v142
	v_lshl_add_u64 v[18:19], v[40:41], 1, s[0:1]
	v_lshlrev_b32_e32 v63, 16, v143
	s_nop 0
	v_lshlrev_b32_e32 v53, 16, v144
	v_lshlrev_b32_e32 v71, 16, v145
	v_lshlrev_b64 v[18:19], 1, v[54:55]
	v_lshl_add_u64 v[40:41], s[30:31], 0, v[18:19]
	v_lshl_add_u64 v[18:19], s[86:87], 0, v[18:19]
	v_lshlrev_b32_e32 v64, 16, v146
	v_lshlrev_b32_e32 v55, 16, v147
	global_store_short_d16_hi v[20:21], v57, off
	v_mul_f32_e32 v20, 0x38800000, v83
	v_mul_f32_e32 v20, v25, v20
	v_fmac_f32_e32 v20, v3, v56
	v_mul_f32_e32 v20, v20, v65
	v_bfe_u32 v21, v20, 16, 1
	v_add3_u32 v20, v20, v21, s45
	global_store_short_d16_hi v[4:5], v20, off
	v_ashrrev_i32_e32 v4, 5, v42
	v_lshl_add_u32 v4, v4, 3, v111
	ds_read_b64 v[4:5], v4 offset:4096
	s_waitcnt lgkmcnt(0)
	v_mul_f32_e32 v4, 0x38800000, v4
	v_mul_f32_e32 v4, v0, v4
	v_fmac_f32_e32 v4, v2, v58
	v_mul_f32_e32 v4, v4, v74
	v_bfe_u32 v20, v4, 16, 1
	v_add3_u32 v4, v4, v20, s45
	global_store_short_d16_hi v[22:23], v4, off
	v_mul_f32_e32 v4, 0x38800000, v5
	v_mul_f32_e32 v4, v25, v4
	v_fmac_f32_e32 v4, v3, v43
	v_mul_f32_e32 v4, v4, v66
	v_bfe_u32 v5, v4, 16, 1
	v_add3_u32 v4, v4, v5, s45
	global_store_short_d16_hi v[6:7], v4, off
	v_ashrrev_i32_e32 v4, 5, v44
	v_lshl_add_u32 v4, v4, 3, v111
	ds_read_b64 v[4:5], v4 offset:8192
	s_waitcnt lgkmcnt(0)
	v_mul_f32_e32 v4, 0x38800000, v4
	v_mul_f32_e32 v4, v0, v4
	v_fmac_f32_e32 v4, v2, v59
	v_mul_f32_e32 v4, v4, v75
	v_bfe_u32 v6, v4, 16, 1
	v_add3_u32 v4, v4, v6, s45
	global_store_short_d16_hi v[30:31], v4, off
	v_mul_f32_e32 v4, 0x38800000, v5
	v_mul_f32_e32 v4, v25, v4
	v_fmac_f32_e32 v4, v3, v45
	v_mul_f32_e32 v4, v4, v67
	v_bfe_u32 v5, v4, 16, 1
	v_add3_u32 v4, v4, v5, s45
	global_store_short_d16_hi v[8:9], v4, off
	v_ashrrev_i32_e32 v4, 5, v46
	v_lshl_add_u32 v4, v4, 3, v111
	ds_read_b64 v[4:5], v4 offset:12288
	s_waitcnt lgkmcnt(0)
	v_mul_f32_e32 v4, 0x38800000, v4
	v_mul_f32_e32 v4, v0, v4
	v_fmac_f32_e32 v4, v2, v60
	v_mul_f32_e32 v4, v4, v76
	v_bfe_u32 v6, v4, 16, 1
	v_add3_u32 v4, v4, v6, s45
	global_store_short_d16_hi v[32:33], v4, off
	v_mul_f32_e32 v4, 0x38800000, v5
	v_mul_f32_e32 v4, v25, v4
	v_fmac_f32_e32 v4, v3, v47
	v_mul_f32_e32 v4, v4, v68
	v_bfe_u32 v5, v4, 16, 1
	v_add3_u32 v4, v4, v5, s45
	global_store_short_d16_hi v[10:11], v4, off
	v_ashrrev_i32_e32 v4, 5, v48
	v_lshl_add_u32 v4, v4, 3, v111
	ds_read_b64 v[4:5], v4 offset:16384
	s_waitcnt lgkmcnt(0)
	v_mul_f32_e32 v4, 0x38800000, v4
	v_mul_f32_e32 v4, v0, v4
	v_fmac_f32_e32 v4, v2, v61
	v_mul_f32_e32 v4, v4, v77
	v_bfe_u32 v6, v4, 16, 1
	v_add3_u32 v4, v4, v6, s45
	global_store_short_d16_hi v[34:35], v4, off
	v_mul_f32_e32 v4, 0x38800000, v5
	v_mul_f32_e32 v4, v25, v4
	v_fmac_f32_e32 v4, v3, v49
	v_mul_f32_e32 v4, v4, v69
	v_bfe_u32 v5, v4, 16, 1
	v_add3_u32 v4, v4, v5, s45
	global_store_short_d16_hi v[12:13], v4, off
	v_ashrrev_i32_e32 v4, 5, v50
	v_lshl_add_u32 v4, v4, 3, v111
	ds_read_b64 v[4:5], v4 offset:20480
	s_waitcnt lgkmcnt(0)
	v_mul_f32_e32 v4, 0x38800000, v4
	v_mul_f32_e32 v4, v0, v4
	v_fmac_f32_e32 v4, v2, v62
	v_mul_f32_e32 v4, v4, v78
	v_bfe_u32 v6, v4, 16, 1
	v_add3_u32 v4, v4, v6, s45
	global_store_short_d16_hi v[36:37], v4, off
	v_mul_f32_e32 v4, 0x38800000, v5
	v_mul_f32_e32 v4, v25, v4
	v_fmac_f32_e32 v4, v3, v51
	v_mul_f32_e32 v4, v4, v70
	v_bfe_u32 v5, v4, 16, 1
	v_add3_u32 v4, v4, v5, s45
	global_store_short_d16_hi v[14:15], v4, off
	v_ashrrev_i32_e32 v4, 5, v52
	v_lshl_add_u32 v4, v4, 3, v111
	ds_read_b64 v[4:5], v4 offset:24576
	s_waitcnt lgkmcnt(0)
	v_mul_f32_e32 v4, 0x38800000, v4
	v_mul_f32_e32 v4, v0, v4
	v_fmac_f32_e32 v4, v2, v63
	v_mul_f32_e32 v4, v4, v79
	v_bfe_u32 v6, v4, 16, 1
	v_add3_u32 v4, v4, v6, s45
	global_store_short_d16_hi v[38:39], v4, off
	v_mul_f32_e32 v4, 0x38800000, v5
	v_mul_f32_e32 v4, v25, v4
	v_fmac_f32_e32 v4, v3, v53
	v_mul_f32_e32 v4, v4, v71
	v_bfe_u32 v5, v4, 16, 1
	v_add3_u32 v4, v4, v5, s45
	global_store_short_d16_hi v[16:17], v4, off
	v_ashrrev_i32_e32 v4, 5, v54
	v_lshl_add_u32 v4, v4, 3, v111
	ds_read_b64 v[4:5], v4 offset:28672
	s_waitcnt lgkmcnt(0)
	v_mul_f32_e32 v4, 0x38800000, v4
	v_mul_f32_e32 v4, v0, v4
	v_fmac_f32_e32 v4, v2, v64
	v_mul_f32_e32 v4, v4, v80
	v_bfe_u32 v6, v4, 16, 1
	v_add3_u32 v4, v4, v6, s45
	global_store_short_d16_hi v[40:41], v4, off
	v_mul_f32_e32 v4, 0x38800000, v5
	v_mul_f32_e32 v4, v25, v4
	v_fmac_f32_e32 v4, v3, v55
	v_mul_f32_e32 v4, v4, v72
	v_bfe_u32 v5, v4, 16, 1
	v_add3_u32 v4, v4, v5, s45
	global_store_short_d16_hi v[18:19], v4, off
	s_cbranch_vccnz .LBB0_704
	v_readlane_b32 s2, v253, 3
	s_add_i32 s33, s33, s2
	s_cmpk_gt_i32 s33, 0x1ff
	s_barrier
	v_readlane_b32 s3, v253, 4
	s_cbranch_scc0 .LBB0_617
